# P1 small_gemm: all 32 operand loads issued up front instead of 3-4 in flight behind vmcnt(0)
# speedup vs baseline: 1.0344x; 1.0111x over previous
.LBB0_109:
	v_lshl_add_u64 v[42:43], v[32:33], 0, v[20:21]
	v_lshl_add_u64 v[44:45], v[30:31], 0, v[20:21]
	s_mov_b32 s7, 0x4400000
	v_add_co_u32_e32 v54, vcc, s7, v42
	s_nop 1
	v_addc_co_u32_e32 v55, vcc, 0, v43, vcc
	s_mov_b32 s7, 0x4410000
	v_add_co_u32_e32 v56, vcc, s7, v42
	s_nop 1
	v_addc_co_u32_e32 v57, vcc, 0, v43, vcc
	s_mov_b32 s7, 0x200000
	v_add_co_u32_e32 v58, vcc, s7, v44
	s_nop 1
	v_addc_co_u32_e32 v59, vcc, 0, v45, vcc
	s_mov_b32 s7, 0x210000
	v_add_co_u32_e32 v60, vcc, s7, v44
	s_nop 1
	v_addc_co_u32_e32 v61, vcc, 0, v45, vcc
	global_load_dwordx4 v[80:83], v[54:55], off
	global_load_dwordx4 v[84:87], v[58:59], off
	global_load_dwordx4 v[88:91], v[60:61], off
	global_load_dwordx4 v[92:95], v[56:57], off
	global_load_dwordx4 v[96:99], v[54:55], off offset:64
	global_load_dwordx4 v[100:103], v[58:59], off offset:64
	global_load_dwordx4 v[104:107], v[60:61], off offset:64
	global_load_dwordx4 v[108:111], v[56:57], off offset:64
	global_load_dwordx4 v[112:115], v[54:55], off offset:128
	global_load_dwordx4 v[116:119], v[58:59], off offset:128
	global_load_dwordx4 v[120:123], v[60:61], off offset:128
	global_load_dwordx4 v[124:127], v[56:57], off offset:128
	global_load_dwordx4 v[128:131], v[54:55], off offset:192
	global_load_dwordx4 v[132:135], v[58:59], off offset:192
	global_load_dwordx4 v[140:143], v[60:61], off offset:192
	global_load_dwordx4 v[144:147], v[56:57], off offset:192
	global_load_dwordx4 v[148:151], v[54:55], off offset:256
	global_load_dwordx4 v[152:155], v[58:59], off offset:256
	global_load_dwordx4 v[156:159], v[60:61], off offset:256
	global_load_dwordx4 v[160:163], v[56:57], off offset:256
	global_load_dwordx4 v[164:167], v[54:55], off offset:320
	global_load_dwordx4 v[172:175], v[58:59], off offset:320
	global_load_dwordx4 v[176:179], v[60:61], off offset:320
	global_load_dwordx4 v[180:183], v[56:57], off offset:320
	global_load_dwordx4 v[184:187], v[54:55], off offset:384
	global_load_dwordx4 v[188:191], v[58:59], off offset:384
	global_load_dwordx4 v[192:195], v[60:61], off offset:384
	global_load_dwordx4 v[196:199], v[56:57], off offset:384
	global_load_dwordx4 v[200:203], v[54:55], off offset:448
	global_load_dwordx4 v[204:207], v[58:59], off offset:448
	global_load_dwordx4 v[208:211], v[60:61], off offset:448
	global_load_dwordx4 v[212:215], v[56:57], off offset:448
	s_waitcnt vmcnt(30)
	v_mfma_f32_16x16x32_bf16 v[4:7], v[80:83], v[84:87], v[4:7]
	s_waitcnt vmcnt(29)
	v_mfma_f32_16x16x32_bf16 v[0:3], v[80:83], v[88:91], v[0:3]
	s_waitcnt vmcnt(28)
	v_mfma_f32_16x16x32_bf16 v[8:11], v[92:95], v[84:87], v[8:11]
	v_mfma_f32_16x16x32_bf16 v[12:15], v[92:95], v[88:91], v[12:15]
	s_waitcnt vmcnt(26)
	v_mfma_f32_16x16x32_bf16 v[4:7], v[96:99], v[100:103], v[4:7]
	s_waitcnt vmcnt(25)
	v_mfma_f32_16x16x32_bf16 v[0:3], v[96:99], v[104:107], v[0:3]
	s_waitcnt vmcnt(24)
	v_mfma_f32_16x16x32_bf16 v[8:11], v[108:111], v[100:103], v[8:11]
	v_mfma_f32_16x16x32_bf16 v[12:15], v[108:111], v[104:107], v[12:15]
	s_waitcnt vmcnt(22)
	v_mfma_f32_16x16x32_bf16 v[4:7], v[112:115], v[116:119], v[4:7]
	s_waitcnt vmcnt(21)
	v_mfma_f32_16x16x32_bf16 v[0:3], v[112:115], v[120:123], v[0:3]
	s_waitcnt vmcnt(20)
	v_mfma_f32_16x16x32_bf16 v[8:11], v[124:127], v[116:119], v[8:11]
	v_mfma_f32_16x16x32_bf16 v[12:15], v[124:127], v[120:123], v[12:15]
	s_waitcnt vmcnt(18)
	v_mfma_f32_16x16x32_bf16 v[4:7], v[128:131], v[132:135], v[4:7]
	s_waitcnt vmcnt(17)
	v_mfma_f32_16x16x32_bf16 v[0:3], v[128:131], v[140:143], v[0:3]
	s_waitcnt vmcnt(16)
	v_mfma_f32_16x16x32_bf16 v[8:11], v[144:147], v[132:135], v[8:11]
	v_mfma_f32_16x16x32_bf16 v[12:15], v[144:147], v[140:143], v[12:15]
	s_waitcnt vmcnt(14)
	v_mfma_f32_16x16x32_bf16 v[4:7], v[148:151], v[152:155], v[4:7]
	s_waitcnt vmcnt(13)
	v_mfma_f32_16x16x32_bf16 v[0:3], v[148:151], v[156:159], v[0:3]
	s_waitcnt vmcnt(12)
	v_mfma_f32_16x16x32_bf16 v[8:11], v[160:163], v[152:155], v[8:11]
	v_mfma_f32_16x16x32_bf16 v[12:15], v[160:163], v[156:159], v[12:15]
	s_waitcnt vmcnt(10)
	v_mfma_f32_16x16x32_bf16 v[4:7], v[164:167], v[172:175], v[4:7]
	s_waitcnt vmcnt(9)
	v_mfma_f32_16x16x32_bf16 v[0:3], v[164:167], v[176:179], v[0:3]
	s_waitcnt vmcnt(8)
	v_mfma_f32_16x16x32_bf16 v[8:11], v[180:183], v[172:175], v[8:11]
	v_mfma_f32_16x16x32_bf16 v[12:15], v[180:183], v[176:179], v[12:15]
	s_waitcnt vmcnt(6)
	v_mfma_f32_16x16x32_bf16 v[4:7], v[184:187], v[188:191], v[4:7]
	s_waitcnt vmcnt(5)
	v_mfma_f32_16x16x32_bf16 v[0:3], v[184:187], v[192:195], v[0:3]
	s_waitcnt vmcnt(4)
	v_mfma_f32_16x16x32_bf16 v[8:11], v[196:199], v[188:191], v[8:11]
	v_mfma_f32_16x16x32_bf16 v[12:15], v[196:199], v[192:195], v[12:15]
	s_waitcnt vmcnt(2)
	v_mfma_f32_16x16x32_bf16 v[4:7], v[200:203], v[204:207], v[4:7]
	s_waitcnt vmcnt(1)
	v_mfma_f32_16x16x32_bf16 v[0:3], v[200:203], v[208:211], v[0:3]
	s_waitcnt vmcnt(0)
	v_mfma_f32_16x16x32_bf16 v[8:11], v[212:215], v[204:207], v[8:11]
	v_mfma_f32_16x16x32_bf16 v[12:15], v[212:215], v[208:211], v[12:15]
	s_nop 0
	s_nop 2
	ds_write2_b32 v40, v4, v0 offset1:16
	ds_write2_b32 v40, v5, v1 offset0:32 offset1:48
	ds_write2_b32 v40, v6, v2 offset0:64 offset1:80
	ds_write2_b32 v40, v7, v3 offset0:96 offset1:112
	v_add_u32_e32 v0, 0x800, v40
	ds_write2_b32 v0, v8, v12 offset1:16
	ds_write2_b32 v0, v9, v13 offset0:32 offset1:48
	ds_write2_b32 v0, v10, v14 offset0:64 offset1:80
	ds_write2_b32 v0, v11, v15 offset0:96 offset1:112
	s_waitcnt lgkmcnt(0)
	s_barrier
	ds_read2st64_b32 v[2:3], v35 offset1:16
	ds_read2st64_b32 v[4:5], v35 offset0:32 offset1:48
	ds_read2st64_b32 v[6:7], v35 offset0:64 offset1:80
	s_lshl_b32 s6, s3, 5
	v_or_b32_e32 v22, s6, v34
	s_waitcnt lgkmcnt(2)
	v_add_f32_e32 v2, 0, v2
	v_add_f32_e32 v8, v2, v3
	ds_read2st64_b32 v[2:3], v35 offset0:96 offset1:112
	s_waitcnt lgkmcnt(2)
	v_add_f32_e32 v4, v8, v4
	v_add_f32_e32 v4, v4, v5
	s_waitcnt lgkmcnt(1)
	v_add_f32_e32 v4, v4, v6
	v_add_f32_e32 v4, v4, v7
	s_waitcnt lgkmcnt(0)
	v_add_f32_e32 v2, v4, v2
	v_ashrrev_i32_e32 v1, 31, v22
	v_mov_b32_e32 v0, v22
	v_add_f32_e32 v6, v2, v3
	v_lshl_add_u64 v[0:1], v[0:1], 1, s[28:29]
	v_bfe_u32 v2, v6, 16, 1
	s_and_b32 s12, s6, 0xfffffc00
	v_add3_u32 v4, v6, v2, s1
	v_lshl_add_u64 v[2:3], v[0:1], 0, v[16:17]
	s_cmpk_lt_i32 s12, 0x800
	global_store_short_d16_hi v[2:3], v4, off
	s_cbranch_scc1 .LBB0_118
	s_cmpk_gt_i32 s12, 0xfff
	s_cbranch_scc0 .LBB0_127
	s_mov_b64 s[10:11], 0
	s_cmpk_eq_i32 s12, 0x1000
	s_mov_b64 s[6:7], 0
	s_cbranch_scc0 .LBB0_114
	s_mov_b64 s[6:7], -1
